# NSA compressed-branch epilogue: gate load hoisted above the 8 partial-result stores with a counted wait (no store drain), on top of v_p11dyn
# baseline (speedup 1.0000x reference)
.LBB0_1501:
	v_mov_b32_e32 v10, v220
	v_mov_b32_e32 v19, v220
	v_ashrrev_i32_e32 v0, 6, v10
	v_lshl_add_u32 v2, v0, 3, s76
	v_lshrrev_b32_e32 v3, 2, v10
	v_and_or_b32 v2, v3, 3, v2
	v_and_or_b32 v1, v10, 3, s7
	v_mul_lo_u32 v2, v2, 48
	v_mad_u32_u24 v2, v1, 3, v2
	v_ashrrev_i32_e32 v3, 31, v2
	v_lshl_add_u64 v[4:5], v[2:3], 2, s[62:63]
	global_load_dword v11, v[4:5], off
	v_mov_b32_e32 v1, v197
	v_mov_b32_e32 v3, v148
	s_nop 0
	v_permlane32_swap_b32_e32 v197, v1
	v_permlane32_swap_b32_e32 v148, v3
	v_add_f32_e32 v5, v197, v1
	v_add_f32_e32 v4, v148, v3
	v_ashrrev_i32_e32 v1, 31, v0
	v_mov_b32_e32 v7, v5
	v_mov_b32_e32 v6, v4
	v_lshlrev_b64 v[0:1], 6, v[0:1]
	v_permlane16_swap_b32_e32 v5, v7
	v_permlane16_swap_b32_e32 v4, v6
	v_lshl_add_u64 v[8:9], v[0:1], 0, s[58:59]
	v_pk_add_f32 v[0:1], v[4:5], v[6:7]
	v_and_or_b32 v8, v10, 63, v8
	v_div_scale_f32 v6, s[14:15], v1, v1, 1.0
	v_lshlrev_b64 v[4:5], 8, v[8:9]
	v_rcp_f32_e32 v8, v6
	v_add_u32_e32 v2, 0xc0, v2
	v_ashrrev_i32_e32 v3, 31, v2
	v_lshl_add_u64 v[14:15], v[2:3], 2, s[62:63]
	v_fma_f32 v2, -v6, v8, 1.0
	v_div_scale_f32 v7, vcc, 1.0, v1, 1.0
	v_fmac_f32_e32 v8, v2, v8
	v_mul_f32_e32 v2, v7, v8
	v_fma_f32 v3, -v6, v2, v7
	v_fmac_f32_e32 v2, v3, v8
	v_fma_f32 v3, -v6, v2, v7
	v_div_fmas_f32 v2, v3, v8, v2
	v_div_fixup_f32 v2, v2, v1, 1.0
	v_cmp_lt_f32_e32 vcc, 0, v1
	s_waitcnt vmcnt(8)
	v_lshl_add_u64 v[116:117], s[64:65], 0, v[4:5]
	v_cndmask_b32_e32 v18, 0, v2, vcc
	s_waitcnt vmcnt(0)
	global_load_dword v1, v[14:15], off
	v_mul_f32_e32 v16, v11, v18
	v_pk_mul_f32 v[4:5], v[86:87], v[16:17] op_sel_hi:[1,0]
	v_pk_mul_f32 v[2:3], v[84:85], v[16:17] op_sel_hi:[1,0]
	v_pk_mul_f32 v[8:9], v[90:91], v[16:17] op_sel_hi:[1,0]
	v_pk_mul_f32 v[6:7], v[88:89], v[16:17] op_sel_hi:[1,0]
	v_pk_mul_f32 v[12:13], v[94:95], v[16:17] op_sel_hi:[1,0]
	v_pk_mul_f32 v[10:11], v[92:93], v[16:17] op_sel_hi:[1,0]
	v_pk_mul_f32 v[86:87], v[98:99], v[16:17] op_sel_hi:[1,0]
	v_pk_mul_f32 v[84:85], v[96:97], v[16:17] op_sel_hi:[1,0]
	v_pk_mul_f32 v[90:91], v[102:103], v[16:17] op_sel_hi:[1,0]
	v_pk_mul_f32 v[88:89], v[100:101], v[16:17] op_sel_hi:[1,0]
	v_pk_mul_f32 v[94:95], v[106:107], v[16:17] op_sel_hi:[1,0]
	v_pk_mul_f32 v[92:93], v[104:105], v[16:17] op_sel_hi:[1,0]
	v_pk_mul_f32 v[98:99], v[110:111], v[16:17] op_sel_hi:[1,0]
	v_pk_mul_f32 v[96:97], v[108:109], v[16:17] op_sel_hi:[1,0]
	v_pk_mul_f32 v[102:103], v[114:115], v[16:17] op_sel_hi:[1,0]
	v_pk_mul_f32 v[100:101], v[112:113], v[16:17] op_sel_hi:[1,0]
	global_store_dwordx4 v[116:117], v[2:5], off
	global_store_dwordx4 v[116:117], v[6:9], off offset:16
	global_store_dwordx4 v[116:117], v[10:13], off offset:32
	global_store_dwordx4 v[116:117], v[84:87], off offset:48
	global_store_dwordx4 v[116:117], v[88:91], off offset:64
	global_store_dwordx4 v[116:117], v[92:95], off offset:80
	global_store_dwordx4 v[116:117], v[96:99], off offset:96
	global_store_dwordx4 v[116:117], v[100:103], off offset:112
	v_div_scale_f32 v2, s[14:15], v0, v0, 1.0
	v_rcp_f32_e32 v3, v2
	v_div_scale_f32 v4, vcc, 1.0, v0, 1.0
	v_fma_f32 v5, -v2, v3, 1.0
	v_fmac_f32_e32 v3, v5, v3
	v_mul_f32_e32 v5, v4, v3
	v_fma_f32 v6, -v2, v5, v4
	v_fmac_f32_e32 v5, v6, v3
	v_fma_f32 v2, -v2, v5, v4
	v_div_fmas_f32 v2, v2, v3, v5
	v_div_fixup_f32 v2, v2, v0, 1.0
	v_cmp_lt_f32_e32 vcc, 0, v0
	s_nop 1
	v_cndmask_b32_e32 v84, 0, v2, vcc
	s_andn2_b64 vcc, exec, s[12:13]
	s_waitcnt vmcnt(8)
	v_mul_f32_e32 v16, v1, v84
	v_pk_mul_f32 v[2:3], v[54:55], v[16:17] op_sel_hi:[1,0]
	v_pk_mul_f32 v[0:1], v[52:53], v[16:17] op_sel_hi:[1,0]
	v_pk_mul_f32 v[52:53], v[68:69], v[16:17] op_sel_hi:[1,0]
	v_pk_mul_f32 v[6:7], v[58:59], v[16:17] op_sel_hi:[1,0]
	v_pk_mul_f32 v[4:5], v[56:57], v[16:17] op_sel_hi:[1,0]
	v_pk_mul_f32 v[10:11], v[62:63], v[16:17] op_sel_hi:[1,0]
	v_pk_mul_f32 v[8:9], v[60:61], v[16:17] op_sel_hi:[1,0]
	v_pk_mul_f32 v[14:15], v[66:67], v[16:17] op_sel_hi:[1,0]
	v_pk_mul_f32 v[12:13], v[64:65], v[16:17] op_sel_hi:[1,0]
	v_pk_mul_f32 v[54:55], v[70:71], v[16:17] op_sel_hi:[1,0]
	v_pk_mul_f32 v[58:59], v[74:75], v[16:17] op_sel_hi:[1,0]
	v_pk_mul_f32 v[56:57], v[72:73], v[16:17] op_sel_hi:[1,0]
	v_pk_mul_f32 v[62:63], v[78:79], v[16:17] op_sel_hi:[1,0]
	v_pk_mul_f32 v[60:61], v[76:77], v[16:17] op_sel_hi:[1,0]
	v_pk_mul_f32 v[66:67], v[82:83], v[16:17] op_sel_hi:[1,0]
	v_pk_mul_f32 v[64:65], v[80:81], v[16:17] op_sel_hi:[1,0]
	global_store_dwordx4 v[116:117], v[0:3], off offset:128
	global_store_dwordx4 v[116:117], v[4:7], off offset:144
	global_store_dwordx4 v[116:117], v[8:11], off offset:160
	global_store_dwordx4 v[116:117], v[12:15], off offset:176
	global_store_dwordx4 v[116:117], v[52:55], off offset:192
	global_store_dwordx4 v[116:117], v[56:59], off offset:208
	global_store_dwordx4 v[116:117], v[60:63], off offset:224
	global_store_dwordx4 v[116:117], v[64:67], off offset:240
	s_nop 0
	v_lshlrev_b32_e32 v52, 5, v19
	v_ashrrev_i32_e32 v53, 31, v52
	s_cbranch_vccnz .LBB0_1503
	v_lshl_add_u64 v[12:13], v[252:253], 0, s[0:1]
	v_lshl_add_u64 v[246:247], v[12:13], 0, s[98:99]
	global_load_dwordx4 v[0:3], v[246:247], off
	global_load_dwordx4 v[4:7], v[246:247], off offset:-4096
	global_load_dwordx4 v[8:11], v[12:13], off
	s_nop 0
	global_load_dwordx4 v[12:15], v[12:13], off offset:-4096
